# scan: per-channel k_a / k_k constants loaded once per chain into spare registers (24 single-dword loads per group removed), counted waits re-derived
# speedup vs baseline: 1.0830x; 1.0026x over previous
.LBB0_302:
	s_mov_b32 s96, 32
	s_barrier
	s_cmp_lt_i32 s96, 0
	s_cbranch_scc1 .LBB0_301
	s_ashr_i32 s22, s95, 4
	s_and_b32 s24, s95, 1
	s_bfe_i32 s33, s95, 0x10000
	s_ashr_i32 s23, s22, 31
	s_cmp_eq_u32 s24, 0
	s_cselect_b64 s[56:57], -1, 0
	s_lshl_b32 s58, s95, 5
	s_and_b32 s33, s33, 0x600
	s_and_b32 s60, s58, 0x1c0
	s_or_b32 s33, s33, s60
	s_lshl_b32 s58, s33, 1
	s_mov_b32 s59, s25
	v_or_b32_e32 v148, s60, v140
	v_lshl_add_u64 v[152:153], v[142:143], 0, s[58:59]
	v_readlane_b32 s58, v244, 15
	v_lshlrev_b32_e32 v6, 1, v148
	v_mov_b32_e32 v7, v34
	v_readlane_b32 s59, v244, 16
	v_or_b32_e32 v2, 0x400, v148
	v_or_b32_e32 v4, 0x408, v148
	v_lshl_add_u64 v[154:155], s[58:59], 0, v[6:7]
	v_readlane_b32 s58, v244, 17
	v_readlane_b32 s59, v244, 18
	v_mov_b32_e32 v32, v34
	v_mov_b32_e32 v33, v34
	v_lshl_add_u64 v[156:157], s[58:59], 0, v[6:7]
	v_mov_b32_e32 v35, v34
	v_lshlrev_b32_e32 v181, 2, v2
	v_lshlrev_b32_e32 v182, 2, v4
	v_mov_b64_e32 v[2:3], v[32:33]
	v_mov_b64_e32 v[6:7], v[32:33]
	v_mov_b64_e32 v[10:11], v[32:33]
	v_mov_b64_e32 v[14:15], v[32:33]
	s_mov_b32 s97, 0
	s_lshl_b64 s[22:23], s[22:23], 11
	v_or_b32_e32 v150, 8, v148
	s_lshl_b32 s24, s24, 15
	s_mov_b32 s76, -4
	s_lshl_b32 s77, s60, 2
	v_mov_b32_e32 v183, v173
	v_mov_b32_e32 v184, v172
	v_mov_b64_e32 v[4:5], v[34:35]
	v_mov_b64_e32 v[8:9], v[34:35]
	v_mov_b64_e32 v[12:13], v[34:35]
	v_mov_b64_e32 v[16:17], v[34:35]
	s_and_saveexec_b64 s[98:99], s[38:39]
	s_cbranch_execz .Lspf_skip0
	s_load_dwordx4 s[64:67], s[80:81], 0x80
	s_lshl_b64 s[58:59], s[2:3], 2
	s_waitcnt lgkmcnt(0)
	s_add_u32 s33, s64, s58
	s_addc_u32 s65, s65, s59
	s_add_u32 s64, s33, s77
	s_addc_u32 s65, s65, 0
	s_add_u32 s33, s66, s58
	s_addc_u32 s58, s67, s59
	s_add_u32 s66, s33, s77
	s_addc_u32 s67, s58, 0
	v_lshlrev_b32_e32 v22, 2, v140
	global_load_dwordx4 v[6:9], v22, s[66:67]
	global_load_dwordx4 v[10:13], v22, s[66:67] offset:16
	global_load_dwordx4 v[14:17], v22, s[66:67] offset:32
	global_load_dwordx4 v[174:177], v22, s[66:67] offset:48
	global_load_dwordx4 v[246:249], v22, s[64:65] offset:32
	global_load_dwordx4 v[250:253], v22, s[64:65] offset:48
	v_lshl_add_u32 v22, s97, 6, v151
	v_sub_u32_e32 v23, 0x7ff, v22
	v_cndmask_b32_e64 v24, v23, v22, s[56:57]
	v_ashrrev_i32_e32 v25, 31, v24
	v_lshl_add_u64 v[22:23], s[22:23], 0, v[24:25]
	v_mov_b64_e32 v[26:27], s[30:31]
	v_mad_u64_u32 v[28:29], s[100:101], v22, s89, v[26:27]
	v_mad_i32_i24 v29, v23, s89, v29
	v_lshlrev_b32_e32 v30, 1, v148
	v_mov_b32_e32 v31, v34
	v_lshl_add_u64 v[28:29], v[28:29], 0, v[30:31]
	s_mov_b64 s[100:101], 0x1000
	v_lshl_add_u64 v[30:31], v[28:29], 0, s[100:101]
	s_mov_b64 s[100:101], 0x3000
	v_lshl_add_u64 v[32:33], v[28:29], 0, s[100:101]
	v_lshl_add_u64 v[22:23], v[22:23], 0, s[24:25]
	v_lshlrev_b64 v[22:23], 10, v[22:23]
	v_lshl_add_u64 v[26:27], v[154:155], 0, v[22:23]
	v_lshl_add_u64 v[22:23], v[156:157], 0, v[22:23]
	v_mov_b32_e32 v56, 0
	v_mov_b32_e32 v57, 0
	v_mov_b32_e32 v58, 0
	v_mov_b32_e32 v59, 0
	v_mov_b32_e32 v60, 0
	v_mov_b32_e32 v61, 0
	v_mov_b32_e32 v62, 0
	v_mov_b32_e32 v63, 0
	v_mov_b32_e32 v68, 0
	v_mov_b32_e32 v69, 0
	v_mov_b32_e32 v70, 0
	v_mov_b32_e32 v71, 0
	v_mov_b32_e32 v72, 0
	v_mov_b32_e32 v73, 0
	v_mov_b32_e32 v74, 0
	v_mov_b32_e32 v75, 0
	v_mov_b32_e32 v92, 0
	v_mov_b32_e32 v93, 0
	v_mov_b32_e32 v94, 0
	v_mov_b32_e32 v95, 0
	v_mov_b32_e32 v96, 0
	v_mov_b32_e32 v97, 0
	v_mov_b32_e32 v98, 0
	v_mov_b32_e32 v99, 0
	v_mov_b32_e32 v100, 0
	v_mov_b32_e32 v101, 0
	v_mov_b32_e32 v102, 0
	v_mov_b32_e32 v103, 0
	v_mov_b32_e32 v104, 0
	v_mov_b32_e32 v105, 0
	v_mov_b32_e32 v106, 0
	v_mov_b32_e32 v107, 0
	global_load_dwordx4 v[84:87], v[30:31], off offset:1024
	global_load_dwordx4 v[88:91], v[30:31], off offset:1040
	global_load_dwordx4 v[52:55], v[30:31], off
	global_load_dwordx4 v[64:67], v[30:31], off offset:2048
	global_load_dwordx4 v[76:79], v[26:27], off
	global_load_dwordx4 v[80:83], v[22:23], off
	v_cmp_lt_i32_e32 vcc, 0, v24
	s_and_saveexec_b64 s[100:101], vcc
	global_load_dwordx4 v[96:99], v[28:29], off offset:-2816
	global_load_dwordx4 v[104:107], v[28:29], off offset:-2800
	global_load_dwordx4 v[56:59], v[28:29], off offset:-3840
	global_load_dwordx4 v[68:71], v[28:29], off offset:-1792
	s_mov_b64 exec, s[100:101]
	v_cmp_gt_i32_e32 vcc, 0x7ff, v24
	s_and_saveexec_b64 s[100:101], vcc
	global_load_dwordx4 v[92:95], v[32:33], off offset:768
	global_load_dwordx4 v[100:103], v[32:33], off offset:784
	global_load_dwordx4 v[60:63], v[32:33], off offset:-256
	global_load_dwordx4 v[72:75], v[32:33], off offset:1792
	s_mov_b64 exec, s[100:101]

.LBB0_331:
	s_or_b64 exec, exec, s[58:59]
	s_lshl_b32 s33, s97, 2
	s_and_b32 s33, s33, 4
	s_lshl_b64 s[58:59], s[62:63], 2
	s_waitcnt lgkmcnt(0)
	s_add_u32 s60, s68, s58
	s_addc_u32 s61, s69, s59
	v_lshlrev_b32_e32 v160, 2, v148
	global_load_dwordx4 v[44:47], v[48:49], off offset:16
	s_nop 0
	global_load_dwordx4 v[48:51], v[50:51], off offset:16
	s_waitcnt vmcnt(8)
	v_cvt_f32_f16_e32 v236, v100
	v_cvt_f32_f16_sdwa v234, v100 dst_sel:DWORD dst_unused:UNUSED_PAD src0_sel:WORD_1
	v_cvt_f32_f16_e32 v232, v101
	v_cvt_f32_f16_sdwa v230, v101 dst_sel:DWORD dst_unused:UNUSED_PAD src0_sel:WORD_1
	v_cvt_f32_f16_e32 v229, v102
	v_cvt_f32_f16_sdwa v227, v102 dst_sel:DWORD dst_unused:UNUSED_PAD src0_sel:WORD_1
	v_cvt_f32_f16_e32 v211, v103
	v_cvt_f32_f16_sdwa v209, v103 dst_sel:DWORD dst_unused:UNUSED_PAD src0_sel:WORD_1
	v_cvt_f32_f16_e32 v109, v92
	v_cvt_f32_f16_sdwa v243, v92 dst_sel:DWORD dst_unused:UNUSED_PAD src0_sel:WORD_1
	v_cvt_f32_f16_e32 v242, v93
	v_cvt_f32_f16_sdwa v205, v93 dst_sel:DWORD dst_unused:UNUSED_PAD src0_sel:WORD_1
	v_cvt_f32_f16_e32 v241, v94
	v_cvt_f32_f16_sdwa v240, v94 dst_sel:DWORD dst_unused:UNUSED_PAD src0_sel:WORD_1
	v_cvt_f32_f16_e32 v239, v95
	v_cvt_f32_f16_sdwa v238, v95 dst_sel:DWORD dst_unused:UNUSED_PAD src0_sel:WORD_1
	global_load_dwordx4 v[92:95], v160, s[60:61] offset:2096
	global_load_dwordx4 v[100:103], v160, s[60:61] offset:2080
	global_load_dwordx4 v[112:115], v160, s[60:61] offset:2064
	global_load_dwordx4 v[128:131], v160, s[60:61] offset:2048
	v_cvt_f32_f16_e32 v235, v104
	v_cvt_f32_f16_sdwa v233, v104 dst_sel:DWORD dst_unused:UNUSED_PAD src0_sel:WORD_1
	v_cvt_f32_f16_e32 v108, v84
	v_cvt_f32_f16_e32 v104, v96
	s_add_u32 s68, s70, s58
	s_addc_u32 s69, s71, s59
	v_cvt_f32_f16_sdwa v196, v96 dst_sel:DWORD dst_unused:UNUSED_PAD src0_sel:WORD_1
	v_sub_f32_e32 v96, v104, v108
	v_cvt_f32_f16_e32 v231, v105
	v_cvt_f32_f16_sdwa v228, v105 dst_sel:DWORD dst_unused:UNUSED_PAD src0_sel:WORD_1
	v_cvt_f32_f16_e32 v226, v106
	v_cvt_f32_f16_sdwa v210, v106 dst_sel:DWORD dst_unused:UNUSED_PAD src0_sel:WORD_1
	v_cvt_f32_f16_e32 v208, v107
	v_cvt_f32_f16_sdwa v206, v107 dst_sel:DWORD dst_unused:UNUSED_PAD src0_sel:WORD_1
	v_cvt_f32_f16_e32 v201, v97
	v_cvt_f32_f16_sdwa v204, v97 dst_sel:DWORD dst_unused:UNUSED_PAD src0_sel:WORD_1
	v_cvt_f32_f16_e32 v203, v98
	v_cvt_f32_f16_sdwa v198, v98 dst_sel:DWORD dst_unused:UNUSED_PAD src0_sel:WORD_1
	v_cvt_f32_f16_e32 v195, v99
	v_cvt_f32_f16_sdwa v237, v99 dst_sel:DWORD dst_unused:UNUSED_PAD src0_sel:WORD_1
	s_lshl_b64 s[58:59], s[2:3], 2
	v_add_u32_e32 v35, s33, v149
	s_add_u32 s33, s64, s58
	s_addc_u32 s65, s65, s59
	s_add_u32 s64, s33, s77
	s_addc_u32 s65, s65, 0
	v_lshlrev_b32_e32 v158, 2, v140
	v_sub_f32_e32 v108, v109, v108
	v_cvt_f32_f16_sdwa v199, v84 dst_sel:DWORD dst_unused:UNUSED_PAD src0_sel:WORD_1
	v_cvt_f32_f16_e32 v200, v85
	v_cvt_f32_f16_sdwa v202, v85 dst_sel:DWORD dst_unused:UNUSED_PAD src0_sel:WORD_1
	v_cvt_f32_f16_e32 v197, v86
	v_cvt_f32_f16_sdwa v194, v86 dst_sel:DWORD dst_unused:UNUSED_PAD src0_sel:WORD_1
	v_cvt_f32_f16_e32 v161, v87
	v_cvt_f32_f16_sdwa v193, v87 dst_sel:DWORD dst_unused:UNUSED_PAD src0_sel:WORD_1
	v_cvt_f32_f16_e32 v192, v88
	v_cvt_f32_f16_sdwa v191, v88 dst_sel:DWORD dst_unused:UNUSED_PAD src0_sel:WORD_1
	v_cvt_f32_f16_e32 v190, v89
	v_cvt_f32_f16_sdwa v189, v89 dst_sel:DWORD dst_unused:UNUSED_PAD src0_sel:WORD_1
	v_cvt_f32_f16_e32 v188, v90
	v_cvt_f32_f16_sdwa v187, v90 dst_sel:DWORD dst_unused:UNUSED_PAD src0_sel:WORD_1
	v_cvt_f32_f16_e32 v186, v91
	v_cvt_f32_f16_sdwa v185, v91 dst_sel:DWORD dst_unused:UNUSED_PAD src0_sel:WORD_1
	v_cmp_lt_i32_e32 vcc, v223, v218
	s_add_u32 s33, s66, s58
	s_addc_u32 s58, s67, s59
	s_add_u32 s66, s33, s77
	s_mov_b32 s33, 0xf800000
	s_addc_u32 s67, s58, 0
	v_lshl_add_u32 v35, v35, 14, 0
	s_waitcnt vmcnt(0)
	v_fma_mix_f32 v159, v96, v128, v84 op_sel_hi:[0,0,1]
	global_load_dwordx4 v[96:99], v160, s[68:69] offset:2096
	global_load_dwordx4 v[104:107], v160, s[68:69] offset:2080
	global_load_dwordx4 v[120:123], v160, s[68:69] offset:2064
	global_load_dwordx4 v[132:135], v160, s[68:69] offset:2048
	v_sub_f32_e32 v128, v196, v199
	v_fma_mix_f32 v196, v128, v129, v84 op_sel:[0,0,1] op_sel_hi:[0,0,1]
	v_sub_f32_e32 v128, v201, v200
	v_fma_mix_f32 v201, v128, v130, v85 op_sel_hi:[0,0,1]
	v_sub_f32_e32 v128, v242, v200
	v_sub_f32_e32 v84, v243, v199
	v_sub_f32_e32 v129, v231, v190
	v_sub_f32_e32 v130, v232, v190
	s_waitcnt vmcnt(0)
	v_fmac_f32_e32 v159, v108, v132
	global_load_dwordx4 v[108:111], v158, s[64:65] offset:48
	global_load_dwordx4 v[116:119], v158, s[64:65] offset:32
	global_load_dwordx4 v[124:127], v158, s[64:65] offset:16
	global_load_dwordx4 v[136:139], v158, s[64:65]
	v_fmac_f32_e32 v201, v128, v134
	v_sub_f32_e32 v128, v204, v202
	v_fma_mix_f32 v204, v128, v131, v85 op_sel:[0,0,1] op_sel_hi:[0,0,1]
	v_sub_f32_e32 v85, v205, v202
	v_fmac_f32_e32 v204, v85, v135
	v_sub_f32_e32 v85, v203, v197
	v_fmac_f32_e32 v196, v84, v133
	v_fma_mix_f32 v202, v85, v112, v86 op_sel_hi:[0,0,1]
	v_sub_f32_e32 v85, v241, v197
	v_fmac_f32_e32 v202, v85, v120
	v_sub_f32_e32 v85, v198, v194
	v_fma_mix_f32 v197, v85, v113, v86 op_sel:[0,0,1] op_sel_hi:[0,0,1]
	v_sub_f32_e32 v85, v240, v194
	v_fmac_f32_e32 v197, v85, v121
	v_sub_f32_e32 v85, v195, v161
	v_fma_mix_f32 v194, v85, v114, v87 op_sel_hi:[0,0,1]
	v_sub_f32_e32 v85, v239, v161
	v_fmac_f32_e32 v194, v85, v122
	v_sub_f32_e32 v85, v237, v193
	v_fma_mix_f32 v161, v85, v115, v87 op_sel:[0,0,1] op_sel_hi:[0,0,1]
	v_sub_f32_e32 v85, v238, v193
	v_sub_f32_e32 v134, v235, v192
	v_fmac_f32_e32 v161, v85, v123
	v_fma_mix_f32 v85, v134, v100, v88 op_sel_hi:[0,0,1]
	v_sub_f32_e32 v133, v236, v192
	v_fmac_f32_e32 v85, v133, v104
	v_sub_f32_e32 v131, v233, v191
	v_sub_f32_e32 v132, v234, v191
	v_sub_f32_e32 v128, v230, v189
	v_sub_f32_e32 v123, v210, v187
	v_sub_f32_e32 v121, v208, v186
	v_sub_f32_e32 v122, v211, v186
	v_sub_f32_e32 v120, v209, v185
	v_cvt_f32_f16_e32 v104, v68
	v_lshl_add_u32 v135, v141, 1, v35
	s_waitcnt vmcnt(2)
	v_mul_f32_e32 v85, v116, v85
	s_waitcnt vmcnt(1)
	v_mul_f32_e32 v203, v124, v202
	s_waitcnt vmcnt(0)
	v_mul_f32_e32 v199, v137, v196
	v_mul_f32_e32 v207, v136, v159
	v_mul_f32_e32 v84, v199, v199
	v_fmac_f32_e32 v84, v207, v207
	v_mul_f32_e32 v200, v138, v201
	v_fmac_f32_e32 v84, v200, v200
	v_mul_f32_e32 v205, v139, v204
	v_fmac_f32_e32 v84, v205, v205
	v_fmac_f32_e32 v84, v203, v203
	v_mul_f32_e32 v198, v125, v197
	v_fmac_f32_e32 v84, v198, v198
	v_mul_f32_e32 v195, v126, v194
	v_fmac_f32_e32 v84, v195, v195
	v_mul_f32_e32 v193, v127, v161
	v_fmac_f32_e32 v84, v193, v193
	v_fmac_f32_e32 v84, v85, v85
	v_fma_mix_f32 v85, v131, v101, v88 op_sel:[0,0,1] op_sel_hi:[0,0,1]
	v_fmac_f32_e32 v85, v132, v105
	v_mul_f32_e32 v85, v117, v85
	v_fmac_f32_e32 v84, v85, v85
	v_fma_mix_f32 v85, v129, v102, v89 op_sel_hi:[0,0,1]
	v_fmac_f32_e32 v85, v130, v106
	v_mul_f32_e32 v85, v118, v85
	v_sub_f32_e32 v127, v228, v189
	v_fmac_f32_e32 v84, v85, v85
	v_fma_mix_f32 v85, v127, v103, v89 op_sel:[0,0,1] op_sel_hi:[0,0,1]
	v_fmac_f32_e32 v85, v128, v107
	v_mul_f32_e32 v85, v119, v85
	v_sub_f32_e32 v125, v226, v188
	v_fmac_f32_e32 v84, v85, v85
	v_fma_mix_f32 v85, v125, v92, v90 op_sel_hi:[0,0,1]
	v_sub_f32_e32 v126, v229, v188
	v_fmac_f32_e32 v85, v126, v96
	v_mul_f32_e32 v85, v108, v85
	v_fmac_f32_e32 v84, v85, v85
	v_fma_mix_f32 v85, v123, v93, v90 op_sel:[0,0,1] op_sel_hi:[0,0,1]
	v_sub_f32_e32 v124, v227, v187
	v_fmac_f32_e32 v85, v124, v97
	v_mul_f32_e32 v85, v109, v85
	v_fmac_f32_e32 v84, v85, v85
	v_fma_mix_f32 v85, v121, v94, v91 op_sel_hi:[0,0,1]
	v_fmac_f32_e32 v85, v122, v98
	v_mul_f32_e32 v85, v110, v85
	v_sub_f32_e32 v119, v206, v185
	v_fmac_f32_e32 v84, v85, v85
	v_fma_mix_f32 v85, v119, v95, v91 op_sel:[0,0,1] op_sel_hi:[0,0,1]
	v_fmac_f32_e32 v85, v120, v99
	v_mul_f32_e32 v85, v111, v85
	v_fmac_f32_e32 v84, v85, v85
	v_cndmask_b32_e32 v85, v217, v223, vcc
	v_lshlrev_b32_e32 v85, 2, v85
	ds_bpermute_b32 v85, v85, v84
	v_cmp_lt_i32_e32 vcc, v224, v218
	v_cvt_f32_f16_e32 v117, v64
	v_cvt_f32_f16_e32 v116, v72
	v_cvt_f32_f16_e32 v137, v76
	s_waitcnt lgkmcnt(0)
	v_add_f32_e32 v84, v84, v85
	v_cndmask_b32_e32 v85, v217, v224, vcc
	v_lshlrev_b32_e32 v85, 2, v85
	ds_bpermute_b32 v85, v85, v84
	v_sub_f32_e32 v104, v104, v117
	v_add3_u32 v206, v35, v178, v179
	s_waitcnt lgkmcnt(0)
	v_add_f32_e32 v84, v84, v85
	v_cmp_gt_f32_e32 vcc, s33, v84
	v_mul_f32_e32 v85, 0x4f800000, v84
	s_nop 0
	v_cndmask_b32_e32 v84, v84, v85, vcc
	v_sqrt_f32_e32 v85, v84
	s_nop 0
	v_add_u32_e32 v86, -1, v85
	v_fma_f32 v87, -v86, v85, v84
	v_cmp_ge_f32_e64 s[58:59], 0, v87
	v_add_u32_e32 v87, 1, v85
	s_nop 0
	v_cndmask_b32_e64 v86, v85, v86, s[58:59]
	v_fma_f32 v85, -v87, v85, v84
	v_cmp_lt_f32_e64 s[58:59], 0, v85
	s_nop 1
	v_cndmask_b32_e64 v85, v86, v87, s[58:59]
	v_mul_f32_e32 v86, 0x37800000, v85
	v_cndmask_b32_e32 v85, v85, v86, vcc
	v_cmp_class_f32_e32 vcc, v84, v214
	s_nop 1
	v_cndmask_b32_e32 v84, v85, v84, vcc
	v_max_f32_e32 v84, 0x2b8cbccc, v84
	v_rcp_f32_e32 v118, v84
	global_load_dwordx4 v[96:99], v160, s[60:61] offset:16
	global_load_dwordx4 v[84:87], v160, s[60:61]
	global_load_dwordx4 v[92:95], v160, s[68:69] offset:16
	global_load_dwordx4 v[88:91], v160, s[68:69]
	global_load_dwordx4 v[100:103], v181, s[60:61] offset:16
	global_load_dwordx4 v[108:111], v181, s[60:61]
	v_mul_f32_e32 v138, v207, v118
	s_waitcnt vmcnt(0)
	v_fma_mix_f32 v208, v104, v108, v64 op_sel_hi:[0,0,1]
	global_load_dwordx4 v[104:107], v181, s[68:69] offset:16
	global_load_dwordx4 v[112:115], v181, s[68:69]
	v_sub_f32_e32 v108, v116, v117
	v_cvt_f32_f16_e32 v116, v80
	s_waitcnt vmcnt(0)
	v_fmac_f32_e32 v208, v108, v112
	v_add_f32_dpp v108, v137, v137 row_shr:1 row_mask:0xf bank_mask:0xf bound_ctrl:1
	v_mul_f32_e32 v112, v138, v116
	v_add_f32_e32 v116, -1.0, v116
	v_add_f32_dpp v108, v108, v108 row_shr:2 row_mask:0xf bank_mask:0xf bound_ctrl:1
	s_waitcnt vmcnt(0)
	v_fma_f32 v116, v116, v6, 1.0
	v_mul_f32_e32 v139, v159, v116
	v_add_f32_dpp v108, v108, v108 row_shr:4 row_mask:0xf bank_mask:0xf bound_ctrl:1
	v_add_u32_e32 v159, v206, v166
	s_nop 0
	v_add_f32_dpp v136, v108, v108 row_shr:8 row_mask:0xf bank_mask:0xf bound_ctrl:1
	s_nop 1
	v_mov_b32_dpp v108, v136 row_newbcast:15 row_mask:0xf bank_mask:0xf bound_ctrl:1
	v_sub_f32_e32 v116, v136, v108
	v_mul_f32_e32 v116, 0x3fb8aa3b, v116
	v_exp_f32_e32 v116, v116
	s_nop 0
	v_mul_f32_e32 v117, v112, v116
	v_mul_f32_e32 v116, v116, v139
	v_cvt_pk_bf16_f32 v117, v117, s0
	v_cvt_pk_bf16_f32 v116, v116, s0
	ds_write_b16 v159, v117 offset:4608
	ds_write_b16 v159, v116 offset:4616
	v_cvt_pk_bf16_f32 v116, v208, s0
	v_add_u32_e32 v117, v135, v167
	ds_write_b16 v117, v116 offset:9728
	s_and_saveexec_b64 s[58:59], s[40:41]
	s_cbranch_execz .LBB0_333
	v_mul_f32_e32 v108, 0xbfb8aa3b, v108
	v_exp_f32_e32 v108, v108
	v_lshl_add_u32 v116, v140, 2, v35
	ds_write_b32 v116, v108 offset:12800
.LBB0_333:
	s_or_b64 exec, exec, s[58:59]
	v_cvt_f32_f16_sdwa v108, v64 dst_sel:DWORD dst_unused:UNUSED_PAD src0_sel:WORD_1
	v_cvt_f32_f16_sdwa v68, v68 dst_sel:DWORD dst_unused:UNUSED_PAD src0_sel:WORD_1
	v_cvt_f32_f16_sdwa v72, v72 dst_sel:DWORD dst_unused:UNUSED_PAD src0_sel:WORD_1
	v_mov_b32_e32 v159, v34
	v_lshl_add_u64 v[116:117], s[66:67], 0, v[158:159]
	v_sub_f32_e32 v68, v68, v108
	v_fma_mix_f32 v207, v68, v109, v64 op_sel:[0,0,1] op_sel_hi:[0,0,1]
	v_sub_f32_e32 v64, v72, v108
	v_fmac_f32_e32 v207, v64, v113
	v_cvt_f32_f16_sdwa v113, v76 dst_sel:DWORD dst_unused:UNUSED_PAD src0_sel:WORD_1
	v_cvt_f32_f16_sdwa v76, v80 dst_sel:DWORD dst_unused:UNUSED_PAD src0_sel:WORD_1
	v_mul_f32_e32 v80, v199, v118
	v_add_u32_e32 v109, v206, v168
	v_add_f32_dpp v64, v113, v113 row_shr:1 row_mask:0xf bank_mask:0xf bound_ctrl:1
	s_nop 1
	v_add_f32_dpp v64, v64, v64 row_shr:2 row_mask:0xf bank_mask:0xf bound_ctrl:1
	s_nop 1
	v_add_f32_dpp v64, v64, v64 row_shr:4 row_mask:0xf bank_mask:0xf bound_ctrl:1
	s_nop 1
	v_add_f32_dpp v68, v64, v64 row_shr:8 row_mask:0xf bank_mask:0xf bound_ctrl:1
	v_mul_f32_e32 v64, v80, v76
	v_add_f32_e32 v76, -1.0, v76
	v_mov_b32_dpp v72, v68 row_newbcast:15 row_mask:0xf bank_mask:0xf bound_ctrl:1
	s_waitcnt vmcnt(0)
	v_fma_f32 v76, v76, v7, 1.0
	v_mul_f32_e32 v196, v196, v76
	v_sub_f32_e32 v76, v68, v72
	v_mul_f32_e32 v76, 0x3fb8aa3b, v76
	v_exp_f32_e32 v76, v76
	s_nop 0
	v_mul_f32_e32 v108, v64, v76
	v_mul_f32_e32 v76, v76, v196
	v_cvt_pk_bf16_f32 v108, v108, s0
	v_cvt_pk_bf16_f32 v76, v76, s0
	ds_write_b16 v109, v108 offset:4608
	ds_write_b16 v109, v76 offset:4616
	v_cvt_pk_bf16_f32 v76, v207, s0
	v_add_u32_e32 v108, v135, v169
	ds_write_b16 v108, v76 offset:9728
	s_and_saveexec_b64 s[58:59], s[40:41]
	s_cbranch_execz .LBB0_335
	v_mul_f32_e32 v72, 0xbfb8aa3b, v72
	v_exp_f32_e32 v72, v72
	v_lshl_add_u32 v76, v140, 2, v35
	ds_write_b32 v76, v72 offset:12804
.LBB0_335:
	s_or_b64 exec, exec, s[58:59]
	v_cvt_f32_f16_e32 v72, v65
	v_cvt_f32_f16_e32 v76, v69
	v_cvt_f32_f16_e32 v199, v73
	v_cvt_f32_f16_e32 v206, v81
	v_mul_f32_e32 v200, v200, v118
	v_sub_f32_e32 v76, v76, v72
	v_sub_f32_e32 v72, v199, v72
	v_cvt_f32_f16_e32 v199, v77
	v_fma_mix_f32 v76, v76, v110, v65 op_sel_hi:[0,0,1]
	v_fmac_f32_e32 v76, v72, v114
	v_mul_f32_e32 v110, v200, v206
	v_add_f32_dpp v72, v199, v199 row_shr:1 row_mask:0xf bank_mask:0xf bound_ctrl:1
	v_add_f32_e32 v206, -1.0, v206
	v_cvt_pk_bf16_f32 v76, v76, s0
	v_add_f32_dpp v72, v72, v72 row_shr:2 row_mask:0xf bank_mask:0xf bound_ctrl:1
	s_waitcnt vmcnt(0)
	v_fma_f32 v206, v206, v8, 1.0
	v_add_f32_dpp v72, v72, v72 row_shr:4 row_mask:0xf bank_mask:0xf bound_ctrl:1
	v_mul_f32_e32 v201, v201, v206
	s_nop 0
	v_add_f32_dpp v114, v72, v72 row_shr:8 row_mask:0xf bank_mask:0xf bound_ctrl:1
	s_nop 1
	v_mov_b32_dpp v72, v114 row_newbcast:15 row_mask:0xf bank_mask:0xf bound_ctrl:1
	v_sub_f32_e32 v206, v114, v72
	v_mul_f32_e32 v206, 0x3fb8aa3b, v206
	v_exp_f32_e32 v206, v206
	s_nop 0
	v_mul_f32_e32 v207, v110, v206
	v_mul_f32_e32 v206, v206, v201
	v_cvt_pk_bf16_f32 v207, v207, s0
	v_cvt_pk_bf16_f32 v206, v206, s0
	ds_write_b16 v109, v207 offset:4688
	ds_write_b16 v109, v206 offset:4696
	ds_write_b16 v108, v76 offset:9776
	s_and_saveexec_b64 s[58:59], s[40:41]
	s_cbranch_execz .LBB0_337
	v_mul_f32_e32 v72, 0xbfb8aa3b, v72
	v_exp_f32_e32 v72, v72
	v_lshl_add_u32 v76, v140, 2, v35
	ds_write_b32 v76, v72 offset:12808
.LBB0_337:
	s_or_b64 exec, exec, s[58:59]
	v_cvt_f32_f16_sdwa v72, v65 dst_sel:DWORD dst_unused:UNUSED_PAD src0_sel:WORD_1
	v_cvt_f32_f16_sdwa v69, v69 dst_sel:DWORD dst_unused:UNUSED_PAD src0_sel:WORD_1
	v_cvt_f32_f16_sdwa v73, v73 dst_sel:DWORD dst_unused:UNUSED_PAD src0_sel:WORD_1
	v_sub_f32_e32 v69, v69, v72
	v_fma_mix_f32 v76, v69, v111, v65 op_sel:[0,0,1] op_sel_hi:[0,0,1]
	v_cvt_f32_f16_sdwa v111, v77 dst_sel:DWORD dst_unused:UNUSED_PAD src0_sel:WORD_1
	v_sub_f32_e32 v65, v73, v72
	v_cvt_f32_f16_sdwa v73, v81 dst_sel:DWORD dst_unused:UNUSED_PAD src0_sel:WORD_1
	v_fmac_f32_e32 v76, v65, v115
	v_add_f32_dpp v65, v111, v111 row_shr:1 row_mask:0xf bank_mask:0xf bound_ctrl:1
	v_mul_f32_e32 v81, v205, v118
	s_nop 0
	v_add_f32_dpp v65, v65, v65 row_shr:2 row_mask:0xf bank_mask:0xf bound_ctrl:1
	s_nop 1
	v_add_f32_dpp v65, v65, v65 row_shr:4 row_mask:0xf bank_mask:0xf bound_ctrl:1
	s_nop 1
	v_add_f32_dpp v69, v65, v65 row_shr:8 row_mask:0xf bank_mask:0xf bound_ctrl:1
	v_mul_f32_e32 v65, v81, v73
	v_add_f32_e32 v73, -1.0, v73
	v_mov_b32_dpp v72, v69 row_newbcast:15 row_mask:0xf bank_mask:0xf bound_ctrl:1
	s_waitcnt vmcnt(0)
	v_fma_f32 v73, v73, v9, 1.0
	v_mul_f32_e32 v115, v204, v73
	v_sub_f32_e32 v73, v69, v72
	v_mul_f32_e32 v73, 0x3fb8aa3b, v73
	v_exp_f32_e32 v73, v73
	s_nop 0
	v_mul_f32_e32 v77, v65, v73
	v_mul_f32_e32 v73, v73, v115
	v_cvt_pk_bf16_f32 v73, v73, s0
	v_cvt_pk_bf16_f32 v77, v77, s0
	ds_write_b16 v109, v73 offset:4776
	v_cvt_pk_bf16_f32 v73, v76, s0
	ds_write_b16 v109, v77 offset:4768
	ds_write_b16 v108, v73 offset:9824
	s_and_saveexec_b64 s[58:59], s[40:41]
	s_cbranch_execz .LBB0_339
	v_mul_f32_e32 v72, 0xbfb8aa3b, v72
	v_exp_f32_e32 v72, v72
	v_lshl_add_u32 v73, v140, 2, v35
	ds_write_b32 v73, v72 offset:12812
.LBB0_339:
	s_or_b64 exec, exec, s[58:59]
	v_cvt_f32_f16_e32 v72, v66
	v_cvt_f32_f16_e32 v73, v70
	v_cvt_f32_f16_e32 v76, v74
	v_cvt_f32_f16_e32 v205, v78
	v_mul_f32_e32 v203, v203, v118
	v_sub_f32_e32 v73, v73, v72
	v_fma_mix_f32 v73, v73, v100, v66 op_sel_hi:[0,0,1]
	v_sub_f32_e32 v72, v76, v72
	v_cvt_f32_f16_e32 v76, v82
	v_fmac_f32_e32 v73, v72, v104
	v_add_f32_dpp v72, v205, v205 row_shr:1 row_mask:0xf bank_mask:0xf bound_ctrl:1
	v_cvt_pk_bf16_f32 v73, v73, s0
	v_mul_f32_e32 v104, v203, v76
	v_add_f32_dpp v72, v72, v72 row_shr:2 row_mask:0xf bank_mask:0xf bound_ctrl:1
	v_add_f32_e32 v76, -1.0, v76
	s_waitcnt vmcnt(0)
	v_fma_f32 v76, v76, v10, 1.0
	v_add_f32_dpp v72, v72, v72 row_shr:4 row_mask:0xf bank_mask:0xf bound_ctrl:1
	v_mul_f32_e32 v202, v202, v76
	s_nop 0
	v_add_f32_dpp v204, v72, v72 row_shr:8 row_mask:0xf bank_mask:0xf bound_ctrl:1
	s_nop 1
	v_mov_b32_dpp v72, v204 row_newbcast:15 row_mask:0xf bank_mask:0xf bound_ctrl:1
	v_sub_f32_e32 v76, v204, v72
	v_mul_f32_e32 v76, 0x3fb8aa3b, v76
	v_exp_f32_e32 v76, v76
	s_nop 0
	v_mul_f32_e32 v77, v104, v76
	v_mul_f32_e32 v76, v76, v202
	v_cvt_pk_bf16_f32 v77, v77, s0
	v_cvt_pk_bf16_f32 v76, v76, s0
	ds_write_b16 v109, v77 offset:4848
	ds_write_b16 v109, v76 offset:4856
	ds_write_b16 v108, v73 offset:9872
	s_and_saveexec_b64 s[58:59], s[40:41]
	s_cbranch_execz .LBB0_341
	v_mul_f32_e32 v72, 0xbfb8aa3b, v72
	v_exp_f32_e32 v72, v72
	v_lshl_add_u32 v73, v140, 2, v35
	ds_write_b32 v73, v72 offset:12816
.LBB0_341:
	s_or_b64 exec, exec, s[58:59]
	v_cvt_f32_f16_sdwa v72, v66 dst_sel:DWORD dst_unused:UNUSED_PAD src0_sel:WORD_1
	v_cvt_f32_f16_sdwa v70, v70 dst_sel:DWORD dst_unused:UNUSED_PAD src0_sel:WORD_1
	v_cvt_f32_f16_sdwa v73, v74 dst_sel:DWORD dst_unused:UNUSED_PAD src0_sel:WORD_1
	v_cvt_f32_f16_sdwa v74, v78 dst_sel:DWORD dst_unused:UNUSED_PAD src0_sel:WORD_1
	v_mul_f32_e32 v78, v198, v118
	v_sub_f32_e32 v70, v70, v72
	v_fma_mix_f32 v76, v70, v101, v66 op_sel:[0,0,1] op_sel_hi:[0,0,1]
	v_sub_f32_e32 v66, v73, v72
	v_cvt_f32_f16_sdwa v73, v82 dst_sel:DWORD dst_unused:UNUSED_PAD src0_sel:WORD_1
	v_fmac_f32_e32 v76, v66, v105
	v_add_f32_dpp v66, v74, v74 row_shr:1 row_mask:0xf bank_mask:0xf bound_ctrl:1
	s_nop 1
	v_add_f32_dpp v66, v66, v66 row_shr:2 row_mask:0xf bank_mask:0xf bound_ctrl:1
	s_nop 1
	v_add_f32_dpp v66, v66, v66 row_shr:4 row_mask:0xf bank_mask:0xf bound_ctrl:1
	s_nop 1
	v_add_f32_dpp v70, v66, v66 row_shr:8 row_mask:0xf bank_mask:0xf bound_ctrl:1
	v_mul_f32_e32 v66, v78, v73
	v_add_f32_e32 v73, -1.0, v73
	v_mov_b32_dpp v72, v70 row_newbcast:15 row_mask:0xf bank_mask:0xf bound_ctrl:1
	s_waitcnt vmcnt(0)
	v_fma_f32 v73, v73, v11, 1.0
	v_mul_f32_e32 v82, v197, v73
	v_sub_f32_e32 v73, v70, v72
	v_mul_f32_e32 v73, 0x3fb8aa3b, v73
	v_exp_f32_e32 v73, v73
	s_nop 0
	v_mul_f32_e32 v77, v66, v73
	v_mul_f32_e32 v73, v73, v82
	v_cvt_pk_bf16_f32 v73, v73, s0
	v_cvt_pk_bf16_f32 v77, v77, s0
	ds_write_b16 v109, v73 offset:4936
	v_cvt_pk_bf16_f32 v73, v76, s0
	ds_write_b16 v109, v77 offset:4928
	ds_write_b16 v108, v73 offset:9920
	s_and_saveexec_b64 s[58:59], s[40:41]
	s_cbranch_execz .LBB0_343
	v_mul_f32_e32 v72, 0xbfb8aa3b, v72
	v_exp_f32_e32 v72, v72
	v_lshl_add_u32 v73, v140, 2, v35
	ds_write_b32 v73, v72 offset:12820
.LBB0_343:
	s_or_b64 exec, exec, s[58:59]
	v_cvt_f32_f16_e32 v72, v67
	v_cvt_f32_f16_e32 v73, v71
	v_cvt_f32_f16_e32 v76, v75
	v_mul_f32_e32 v195, v195, v118
	v_sub_f32_e32 v73, v73, v72
	v_fma_mix_f32 v73, v73, v102, v67 op_sel_hi:[0,0,1]
	v_sub_f32_e32 v72, v76, v72
	v_fmac_f32_e32 v73, v72, v106
	v_cvt_f32_f16_e32 v106, v79
	v_cvt_f32_f16_e32 v76, v83
	v_cvt_pk_bf16_f32 v73, v73, s0
	v_add_f32_dpp v72, v106, v106 row_shr:1 row_mask:0xf bank_mask:0xf bound_ctrl:1
	v_mul_f32_e32 v102, v195, v76
	s_nop 0
	v_add_f32_dpp v72, v72, v72 row_shr:2 row_mask:0xf bank_mask:0xf bound_ctrl:1
	v_add_f32_e32 v76, -1.0, v76
	s_waitcnt vmcnt(0)
	v_fma_f32 v76, v76, v12, 1.0
	v_add_f32_dpp v72, v72, v72 row_shr:4 row_mask:0xf bank_mask:0xf bound_ctrl:1
	v_mul_f32_e32 v194, v194, v76
	s_nop 0
	v_add_f32_dpp v105, v72, v72 row_shr:8 row_mask:0xf bank_mask:0xf bound_ctrl:1
	s_nop 1
	v_mov_b32_dpp v72, v105 row_newbcast:15 row_mask:0xf bank_mask:0xf bound_ctrl:1
	v_sub_f32_e32 v76, v105, v72
	v_mul_f32_e32 v76, 0x3fb8aa3b, v76
	v_exp_f32_e32 v76, v76
	s_nop 0
	v_mul_f32_e32 v77, v102, v76
	v_mul_f32_e32 v76, v76, v194
	v_cvt_pk_bf16_f32 v77, v77, s0
	v_cvt_pk_bf16_f32 v76, v76, s0
	ds_write_b16 v109, v77 offset:5008
	ds_write_b16 v109, v76 offset:5016
	ds_write_b16 v108, v73 offset:9968
	s_and_saveexec_b64 s[58:59], s[40:41]
	s_cbranch_execz .LBB0_345
	v_mul_f32_e32 v72, 0xbfb8aa3b, v72
	v_exp_f32_e32 v72, v72
	v_lshl_add_u32 v73, v140, 2, v35
	ds_write_b32 v73, v72 offset:12824
.LBB0_345:
	s_or_b64 exec, exec, s[58:59]
	v_cvt_f32_f16_sdwa v72, v67 dst_sel:DWORD dst_unused:UNUSED_PAD src0_sel:WORD_1
	v_cvt_f32_f16_sdwa v71, v71 dst_sel:DWORD dst_unused:UNUSED_PAD src0_sel:WORD_1
	v_cvt_f32_f16_sdwa v73, v75 dst_sel:DWORD dst_unused:UNUSED_PAD src0_sel:WORD_1
	v_cvt_f32_f16_sdwa v75, v79 dst_sel:DWORD dst_unused:UNUSED_PAD src0_sel:WORD_1
	v_mul_f32_e32 v79, v193, v118
	v_sub_f32_e32 v71, v71, v72
	v_fma_mix_f32 v76, v71, v103, v67 op_sel:[0,0,1] op_sel_hi:[0,0,1]
	v_sub_f32_e32 v67, v73, v72
	v_cvt_f32_f16_sdwa v73, v83 dst_sel:DWORD dst_unused:UNUSED_PAD src0_sel:WORD_1
	v_fmac_f32_e32 v76, v67, v107
	v_add_f32_dpp v67, v75, v75 row_shr:1 row_mask:0xf bank_mask:0xf bound_ctrl:1
	s_nop 1
	v_add_f32_dpp v67, v67, v67 row_shr:2 row_mask:0xf bank_mask:0xf bound_ctrl:1
	s_nop 1
	v_add_f32_dpp v67, v67, v67 row_shr:4 row_mask:0xf bank_mask:0xf bound_ctrl:1
	s_nop 1
	v_add_f32_dpp v71, v67, v67 row_shr:8 row_mask:0xf bank_mask:0xf bound_ctrl:1
	v_mul_f32_e32 v67, v79, v73
	v_add_f32_e32 v73, -1.0, v73
	v_mov_b32_dpp v72, v71 row_newbcast:15 row_mask:0xf bank_mask:0xf bound_ctrl:1
	s_waitcnt vmcnt(0)
	v_fma_f32 v73, v73, v13, 1.0
	v_mul_f32_e32 v83, v161, v73
	v_sub_f32_e32 v73, v71, v72
	v_mul_f32_e32 v73, 0x3fb8aa3b, v73
	v_exp_f32_e32 v73, v73
	s_nop 0
	v_mul_f32_e32 v77, v67, v73
	v_mul_f32_e32 v73, v73, v83
	v_cvt_pk_bf16_f32 v73, v73, s0
	v_cvt_pk_bf16_f32 v77, v77, s0
	ds_write_b16 v109, v73 offset:5096
	v_cvt_pk_bf16_f32 v73, v76, s0
	ds_write_b16 v109, v77 offset:5088
	ds_write_b16 v108, v73 offset:10016
	s_and_saveexec_b64 s[58:59], s[40:41]
	s_cbranch_execz .LBB0_347
	v_mul_f32_e32 v72, 0xbfb8aa3b, v72
	v_exp_f32_e32 v72, v72
	v_lshl_add_u32 v73, v140, 2, v35
	ds_write_b32 v73, v72 offset:12828
.LBB0_347:
	s_or_b64 exec, exec, s[58:59]
	v_cvt_f32_f16_sdwa v103, v55 dst_sel:DWORD dst_unused:UNUSED_PAD src0_sel:WORD_1
	v_cvt_f32_f16_sdwa v107, v59 dst_sel:DWORD dst_unused:UNUSED_PAD src0_sel:WORD_1
	v_lshl_add_u64 v[100:101], s[64:65], 0, v[158:159]
	v_cvt_f32_f16_sdwa v158, v63 dst_sel:DWORD dst_unused:UNUSED_PAD src0_sel:WORD_1
	v_sub_f32_e32 v75, v75, v71
	v_sub_f32_e32 v107, v107, v103
	v_fma_mix_f32 v99, v107, v99, v55 op_sel:[0,0,1] op_sel_hi:[0,0,1]
	v_sub_f32_e32 v103, v158, v103
	v_fmac_f32_e32 v99, v103, v95
	v_mul_f32_e32 v95, 0x3fb8aa3b, v71
	v_mul_f32_e32 v75, 0x3fb8aa3b, v75
	v_exp_f32_e32 v95, v95
	v_exp_f32_e32 v75, v75
	v_cvt_f32_f16_e32 v59, v59
	v_cvt_f32_f16_e32 v63, v63
	v_mul_f32_e32 v67, v67, v95
	v_mul_f32_e32 v75, v79, v75
	v_mul_f32_e32 v79, v95, v83
	v_cvt_f32_f16_e32 v83, v55
	v_cvt_f32_f16_sdwa v95, v58 dst_sel:DWORD dst_unused:UNUSED_PAD src0_sel:WORD_1
	v_sub_f32_e32 v74, v74, v70
	v_mul_f32_e32 v74, 0x3fb8aa3b, v74
	v_sub_f32_e32 v59, v59, v83
	v_fma_mix_f32 v55, v59, v98, v55 op_sel_hi:[0,0,1]
	v_sub_f32_e32 v59, v63, v83
	v_mul_f32_e32 v83, 0xbfb8aa3b, v105
	v_exp_f32_e32 v83, v83
	v_fmac_f32_e32 v55, v59, v94
	v_cvt_f32_f16_sdwa v98, v62 dst_sel:DWORD dst_unused:UNUSED_PAD src0_sel:WORD_1
	v_exp_f32_e32 v74, v74
	v_mul_f32_e32 v83, v55, v83
	v_cvt_f32_f16_sdwa v55, v54 dst_sel:DWORD dst_unused:UNUSED_PAD src0_sel:WORD_1
	v_cvt_f32_f16_e32 v58, v58
	v_mul_f32_e32 v74, v78, v74
	v_cvt_f32_f16_e32 v62, v62
	v_sub_f32_e32 v95, v95, v55
	v_fma_mix_f32 v95, v95, v97, v54 op_sel:[0,0,1] op_sel_hi:[0,0,1]
	v_sub_f32_e32 v55, v98, v55
	v_fmac_f32_e32 v95, v55, v93
	v_mul_f32_e32 v55, 0x3fb8aa3b, v70
	v_exp_f32_e32 v55, v55
	v_cvt_f32_f16_sdwa v93, v61 dst_sel:DWORD dst_unused:UNUSED_PAD src0_sel:WORD_1
	v_mul_f32_e32 v59, 0x3fb8aa3b, v105
	v_exp_f32_e32 v59, v59
	v_mul_f32_e32 v66, v66, v55
	v_mul_f32_e32 v78, v55, v82
	v_cvt_f32_f16_e32 v55, v54
	v_mul_f32_e32 v94, v102, v59
	v_sub_f32_e32 v63, v106, v105
	v_mul_f32_e32 v63, 0x3fb8aa3b, v63
	v_sub_f32_e32 v58, v58, v55
	v_fma_mix_f32 v54, v58, v96, v54 op_sel_hi:[0,0,1]
	v_sub_f32_e32 v55, v62, v55
	v_fmac_f32_e32 v54, v55, v92
	v_mul_f32_e32 v55, 0x3fb8aa3b, v204
	v_mul_f32_e32 v62, 0xbfb8aa3b, v204
	v_exp_f32_e32 v55, v55
	v_exp_f32_e32 v62, v62
	v_sub_f32_e32 v58, v205, v204
	v_mul_f32_e32 v58, 0x3fb8aa3b, v58
	v_mul_f32_e32 v82, v104, v55
	v_mul_f32_e32 v62, v54, v62
	v_mul_f32_e32 v92, v55, v202
	v_cvt_f32_f16_sdwa v54, v53 dst_sel:DWORD dst_unused:UNUSED_PAD src0_sel:WORD_1
	v_cvt_f32_f16_sdwa v55, v57 dst_sel:DWORD dst_unused:UNUSED_PAD src0_sel:WORD_1
	v_mul_f32_e32 v71, 0xbfb8aa3b, v71
	v_exp_f32_e32 v63, v63
	v_mul_f32_e32 v70, 0xbfb8aa3b, v70
	v_sub_f32_e32 v55, v55, v54
	v_fma_mix_f32 v55, v55, v87, v53 op_sel:[0,0,1] op_sel_hi:[0,0,1]
	v_sub_f32_e32 v54, v93, v54
	v_sub_f32_e32 v87, v111, v69
	v_fmac_f32_e32 v55, v54, v91
	v_mul_f32_e32 v54, 0x3fb8aa3b, v69
	v_mul_f32_e32 v87, 0x3fb8aa3b, v87
	v_mul_f32_e32 v69, 0xbfb8aa3b, v69
	v_exp_f32_e32 v54, v54
	v_exp_f32_e32 v87, v87
	v_exp_f32_e32 v69, v69
	v_exp_f32_e32 v58, v58
	v_mul_f32_e32 v65, v65, v54
	v_mul_f32_e32 v81, v81, v87
	v_mul_f32_e32 v69, v55, v69
	v_mul_f32_e32 v87, v54, v115
	v_cvt_f32_f16_e32 v54, v53
	v_cvt_f32_f16_e32 v55, v57
	v_cvt_f32_f16_e32 v57, v61
	v_exp_f32_e32 v71, v71
	v_exp_f32_e32 v70, v70
	v_sub_f32_e32 v55, v55, v54
	v_fma_mix_f32 v53, v55, v86, v53 op_sel_hi:[0,0,1]
	v_sub_f32_e32 v54, v57, v54
	v_fmac_f32_e32 v53, v54, v90
	v_mul_f32_e32 v54, 0x3fb8aa3b, v114
	v_mul_f32_e32 v57, 0xbfb8aa3b, v114
	v_exp_f32_e32 v54, v54
	v_exp_f32_e32 v57, v57
	v_cvt_f32_f16_sdwa v90, v60 dst_sel:DWORD dst_unused:UNUSED_PAD src0_sel:WORD_1
	v_sub_f32_e32 v55, v199, v114
	v_mul_f32_e32 v61, v110, v54
	v_mul_f32_e32 v57, v53, v57
	v_mul_f32_e32 v86, v54, v201
	v_cvt_f32_f16_sdwa v53, v52 dst_sel:DWORD dst_unused:UNUSED_PAD src0_sel:WORD_1
	v_cvt_f32_f16_sdwa v54, v56 dst_sel:DWORD dst_unused:UNUSED_PAD src0_sel:WORD_1
	v_mul_f32_e32 v55, 0x3fb8aa3b, v55
	v_exp_f32_e32 v55, v55
	v_mul_f32_e32 v63, v195, v63
	v_sub_f32_e32 v54, v54, v53
	v_fma_mix_f32 v54, v54, v85, v52 op_sel:[0,0,1] op_sel_hi:[0,0,1]
	v_sub_f32_e32 v53, v90, v53
	v_fmac_f32_e32 v54, v53, v89
	v_mul_f32_e32 v53, 0x3fb8aa3b, v68
	v_sub_f32_e32 v85, v113, v68
	v_mul_f32_e32 v68, 0xbfb8aa3b, v68
	v_mul_f32_e32 v85, 0x3fb8aa3b, v85
	v_exp_f32_e32 v68, v68
	v_exp_f32_e32 v53, v53
	v_exp_f32_e32 v85, v85
	v_mul_f32_e32 v58, v203, v58
	v_mul_f32_e32 v68, v54, v68
	v_cvt_f32_f16_e32 v54, v56
	v_cvt_f32_f16_e32 v56, v52
	v_mul_f32_e32 v80, v80, v85
	v_mul_f32_e32 v64, v64, v53
	v_mul_f32_e32 v85, v53, v196
	v_lshlrev_b32_e32 v53, 1, v140
	v_add3_u32 v102, v135, v171, v53
	v_cvt_f32_f16_e32 v53, v60
	v_sub_f32_e32 v54, v54, v56
	v_fma_mix_f32 v52, v54, v84, v52 op_sel_hi:[0,0,1]
	v_sub_f32_e32 v54, v137, v136
	v_sub_f32_e32 v53, v53, v56
	v_mul_f32_e32 v54, 0x3fb8aa3b, v54
	v_fmac_f32_e32 v52, v53, v88
	v_mul_f32_e32 v53, 0x3fb8aa3b, v136
	v_exp_f32_e32 v54, v54
	v_mul_f32_e32 v56, 0xbfb8aa3b, v136
	v_exp_f32_e32 v53, v53
	v_exp_f32_e32 v56, v56
	v_mul_f32_e32 v55, v200, v55
	v_mul_f32_e32 v54, v138, v54
	v_mul_f32_e32 v71, v99, v71
	v_mul_f32_e32 v70, v95, v70
	v_mul_f32_e32 v56, v52, v56
	v_mul_f32_e32 v60, v112, v53
	v_mul_f32_e32 v84, v53, v139
	v_cvt_pk_bf16_f32 v52, v54, v80
	v_cvt_pk_bf16_f32 v53, v55, v81
	v_cvt_pk_bf16_f32 v54, v58, v74
	v_cvt_pk_bf16_f32 v55, v63, v75
	ds_write_b128 v102, v[52:55]
	v_cvt_pk_bf16_f32 v52, v56, v68
	v_cvt_pk_bf16_f32 v53, v57, v69
	v_cvt_pk_bf16_f32 v54, v62, v70
	v_cvt_pk_bf16_f32 v55, v83, v71
	v_mov_b32_e32 v161, v34
	v_mul_f32_e32 v59, v59, v194
	ds_write_b128 v102, v[52:55] offset:2304
	v_cvt_pk_bf16_f32 v52, v60, v64
	v_cvt_pk_bf16_f32 v53, v61, v65
	v_cvt_pk_bf16_f32 v54, v82, v66
	v_cvt_pk_bf16_f32 v55, v94, v67
	v_lshl_add_u64 v[72:73], s[60:61], 0, v[160:161]
	v_lshl_add_u64 v[76:77], s[68:69], 0, v[160:161]
	ds_write_b128 v162, v[52:55]
	v_cvt_pk_bf16_f32 v52, v84, v85
	v_cvt_pk_bf16_f32 v53, v86, v87
	v_cvt_pk_bf16_f32 v54, v92, v78
	v_cvt_pk_bf16_f32 v55, v59, v79
	ds_write_b128 v162, v[52:55] offset:2304
	global_load_dwordx4 v[64:67], v[72:73], off offset:48
	global_load_dwordx4 v[56:59], v[72:73], off offset:32
	global_load_dwordx4 v[60:63], v[76:77], off offset:48
	global_load_dwordx4 v[52:55], v[76:77], off offset:32
	global_load_dwordx4 v[68:71], v[72:73], off offset:2096
	global_load_dwordx4 v[84:87], v[72:73], off offset:2080
	s_nop 0
	global_load_dwordx4 v[72:75], v[76:77], off offset:2096
	global_load_dwordx4 v[88:91], v[76:77], off offset:2080
	s_nop 0
	global_load_dwordx4 v[76:79], v182, s[60:61] offset:16
	global_load_dwordx4 v[92:95], v182, s[60:61]
	v_cvt_f32_f16_e32 v80, v36
	v_cvt_f32_f16_e32 v103, v48
	s_waitcnt vmcnt(4)
	v_fmac_f32_e32 v192, v134, v84
	s_waitcnt vmcnt(2)
	v_fmac_f32_e32 v192, v133, v88
	v_cvt_f32_f16_e32 v88, v30
	v_cvt_f32_f16_e32 v84, v40
	v_sub_f32_e32 v80, v80, v88
	s_waitcnt vmcnt(0)
	v_fma_mix_f32 v105, v80, v92, v30 op_sel_hi:[0,0,1]
	global_load_dwordx4 v[80:83], v182, s[68:69] offset:16
	global_load_dwordx4 v[96:99], v182, s[68:69]
	v_sub_f32_e32 v84, v84, v88
	v_cvt_f32_f16_e32 v88, v44
	s_waitcnt vmcnt(0)
	v_fmac_f32_e32 v105, v84, v96
	v_add_f32_dpp v84, v88, v88 row_shr:1 row_mask:0xf bank_mask:0xf bound_ctrl:1
	v_cvt_pk_bf16_f32 v105, v105, s0
	s_nop 0
	v_add_f32_dpp v84, v84, v84 row_shr:2 row_mask:0xf bank_mask:0xf bound_ctrl:1
	s_nop 1
	v_add_f32_dpp v84, v84, v84 row_shr:4 row_mask:0xf bank_mask:0xf bound_ctrl:1
	s_nop 1
	v_add_f32_dpp v92, v84, v84 row_shr:8 row_mask:0xf bank_mask:0xf bound_ctrl:1
	s_waitcnt vmcnt(0)
	v_mul_f32_e32 v84, v192, v246
	v_mul_f32_e32 v96, v118, v84
	v_mov_b32_dpp v104, v92 row_newbcast:15 row_mask:0xf bank_mask:0xf bound_ctrl:1
	v_mul_f32_e32 v84, v96, v103
	v_add_f32_e32 v103, -1.0, v103
	v_fma_f32 v103, v103, v14, 1.0
	v_sub_f32_e32 v106, v92, v104
	v_mul_f32_e32 v106, 0x3fb8aa3b, v106
	v_exp_f32_e32 v106, v106
	v_mul_f32_e32 v103, v192, v103
	v_mul_f32_e32 v107, v106, v84
	v_mul_f32_e32 v106, v106, v103
	v_cvt_pk_bf16_f32 v107, v107, s0
	v_cvt_pk_bf16_f32 v106, v106, s0
	ds_write_b16 v109, v107 offset:5168
	ds_write_b16 v109, v106 offset:5176
	ds_write_b16 v108, v105 offset:10064
	s_and_saveexec_b64 s[58:59], s[40:41]
	s_cbranch_execz .LBB0_349
	v_mul_f32_e32 v104, 0xbfb8aa3b, v104
	v_exp_f32_e32 v104, v104
	v_lshl_add_u32 v105, v140, 2, v35
	ds_write_b32 v105, v104 offset:12832
.LBB0_349:
	s_or_b64 exec, exec, s[58:59]
	v_fmac_f32_e32 v191, v131, v85
	v_cvt_f32_f16_sdwa v85, v30 dst_sel:DWORD dst_unused:UNUSED_PAD src0_sel:WORD_1
	v_cvt_f32_f16_sdwa v36, v36 dst_sel:DWORD dst_unused:UNUSED_PAD src0_sel:WORD_1
	v_cvt_f32_f16_sdwa v40, v40 dst_sel:DWORD dst_unused:UNUSED_PAD src0_sel:WORD_1
	v_fmac_f32_e32 v191, v132, v89
	v_cvt_f32_f16_sdwa v48, v48 dst_sel:DWORD dst_unused:UNUSED_PAD src0_sel:WORD_1
	v_sub_f32_e32 v36, v36, v85
	v_fma_mix_f32 v89, v36, v93, v30 op_sel:[0,0,1] op_sel_hi:[0,0,1]
	v_sub_f32_e32 v30, v40, v85
	v_cvt_f32_f16_sdwa v36, v44 dst_sel:DWORD dst_unused:UNUSED_PAD src0_sel:WORD_1
	v_fmac_f32_e32 v89, v30, v97
	v_cvt_pk_bf16_f32 v89, v89, s0
	v_add_f32_dpp v30, v36, v36 row_shr:1 row_mask:0xf bank_mask:0xf bound_ctrl:1
	s_waitcnt vmcnt(0)
	v_mul_f32_e32 v40, v191, v247
	v_add_f32_dpp v30, v30, v30 row_shr:2 row_mask:0xf bank_mask:0xf bound_ctrl:1
	v_mul_f32_e32 v44, v118, v40
	v_mul_f32_e32 v40, v44, v48
	v_add_f32_dpp v30, v30, v30 row_shr:4 row_mask:0xf bank_mask:0xf bound_ctrl:1
	v_add_f32_e32 v48, -1.0, v48
	s_waitcnt vmcnt(0)
	v_fma_f32 v48, v48, v15, 1.0
	v_add_f32_dpp v30, v30, v30 row_shr:8 row_mask:0xf bank_mask:0xf bound_ctrl:1
	v_mul_f32_e32 v48, v191, v48
	s_nop 0
	v_mov_b32_dpp v85, v30 row_newbcast:15 row_mask:0xf bank_mask:0xf bound_ctrl:1
	v_sub_f32_e32 v93, v30, v85
	v_mul_f32_e32 v93, 0x3fb8aa3b, v93
	v_exp_f32_e32 v93, v93
	s_nop 0
	v_mul_f32_e32 v97, v93, v40
	v_mul_f32_e32 v93, v93, v48
	v_cvt_pk_bf16_f32 v97, v97, s0
	v_cvt_pk_bf16_f32 v93, v93, s0
	ds_write_b16 v109, v97 offset:5248
	ds_write_b16 v109, v93 offset:5256
	ds_write_b16 v108, v89 offset:10112
	s_and_saveexec_b64 s[58:59], s[40:41]
	s_cbranch_execz .LBB0_351
	v_mul_f32_e32 v85, 0xbfb8aa3b, v85
	v_exp_f32_e32 v85, v85
	v_lshl_add_u32 v89, v140, 2, v35
	ds_write_b32 v89, v85 offset:12836
.LBB0_351:
	s_or_b64 exec, exec, s[58:59]
	v_fmac_f32_e32 v190, v129, v86
	v_cvt_f32_f16_e32 v85, v31
	v_cvt_f32_f16_e32 v86, v37
	v_cvt_f32_f16_e32 v89, v41
	v_cvt_f32_f16_e32 v93, v49
	v_fmac_f32_e32 v190, v130, v90
	v_sub_f32_e32 v86, v86, v85
	v_sub_f32_e32 v85, v89, v85
	v_fma_mix_f32 v97, v86, v94, v31 op_sel_hi:[0,0,1]
	v_fmac_f32_e32 v97, v85, v98
	v_cvt_f32_f16_e32 v86, v45
	v_cvt_pk_bf16_f32 v97, v97, s0
	s_waitcnt vmcnt(0)
	v_mul_f32_e32 v89, v190, v248
	v_add_f32_dpp v85, v86, v86 row_shr:1 row_mask:0xf bank_mask:0xf bound_ctrl:1
	v_mul_f32_e32 v90, v118, v89
	v_mul_f32_e32 v89, v90, v93
	v_add_f32_dpp v85, v85, v85 row_shr:2 row_mask:0xf bank_mask:0xf bound_ctrl:1
	v_add_f32_e32 v93, -1.0, v93
	s_waitcnt vmcnt(0)
	v_fma_f32 v93, v93, v16, 1.0
	v_add_f32_dpp v85, v85, v85 row_shr:4 row_mask:0xf bank_mask:0xf bound_ctrl:1
	v_mul_f32_e32 v93, v190, v93
	s_nop 0
	v_add_f32_dpp v85, v85, v85 row_shr:8 row_mask:0xf bank_mask:0xf bound_ctrl:1
	s_nop 1
	v_mov_b32_dpp v94, v85 row_newbcast:15 row_mask:0xf bank_mask:0xf bound_ctrl:1
	v_sub_f32_e32 v98, v85, v94
	v_mul_f32_e32 v98, 0x3fb8aa3b, v98
	v_exp_f32_e32 v98, v98
	s_nop 0
	v_mul_f32_e32 v104, v98, v89
	v_mul_f32_e32 v98, v98, v93
	v_cvt_pk_bf16_f32 v104, v104, s0
	v_cvt_pk_bf16_f32 v98, v98, s0
	ds_write_b16 v109, v104 offset:5328
	ds_write_b16 v109, v98 offset:5336
	ds_write_b16 v108, v97 offset:10160
	s_and_saveexec_b64 s[58:59], s[40:41]
	s_cbranch_execz .LBB0_353
	v_mul_f32_e32 v94, 0xbfb8aa3b, v94
	v_exp_f32_e32 v94, v94
	v_lshl_add_u32 v97, v140, 2, v35
	ds_write_b32 v97, v94 offset:12840
.LBB0_353:
	s_or_b64 exec, exec, s[58:59]
	v_fmac_f32_e32 v189, v127, v87
	v_cvt_f32_f16_sdwa v87, v31 dst_sel:DWORD dst_unused:UNUSED_PAD src0_sel:WORD_1
	v_cvt_f32_f16_sdwa v37, v37 dst_sel:DWORD dst_unused:UNUSED_PAD src0_sel:WORD_1
	v_cvt_f32_f16_sdwa v41, v41 dst_sel:DWORD dst_unused:UNUSED_PAD src0_sel:WORD_1
	v_fmac_f32_e32 v189, v128, v91
	v_sub_f32_e32 v37, v37, v87
	v_fma_mix_f32 v91, v37, v95, v31 op_sel:[0,0,1] op_sel_hi:[0,0,1]
	v_sub_f32_e32 v31, v41, v87
	v_cvt_f32_f16_sdwa v37, v45 dst_sel:DWORD dst_unused:UNUSED_PAD src0_sel:WORD_1
	v_fmac_f32_e32 v91, v31, v99
	v_cvt_f32_f16_sdwa v49, v49 dst_sel:DWORD dst_unused:UNUSED_PAD src0_sel:WORD_1
	v_cvt_pk_bf16_f32 v91, v91, s0
	v_add_f32_dpp v31, v37, v37 row_shr:1 row_mask:0xf bank_mask:0xf bound_ctrl:1
	s_waitcnt vmcnt(0)
	v_mul_f32_e32 v41, v189, v249
	v_add_f32_dpp v31, v31, v31 row_shr:2 row_mask:0xf bank_mask:0xf bound_ctrl:1
	v_mul_f32_e32 v45, v118, v41
	v_mul_f32_e32 v41, v45, v49
	v_add_f32_dpp v31, v31, v31 row_shr:4 row_mask:0xf bank_mask:0xf bound_ctrl:1
	v_add_f32_e32 v49, -1.0, v49
	v_fma_f32 v49, v49, v17, 1.0
	v_add_f32_dpp v31, v31, v31 row_shr:8 row_mask:0xf bank_mask:0xf bound_ctrl:1
	v_mul_f32_e32 v49, v189, v49
	s_nop 0
	v_mov_b32_dpp v87, v31 row_newbcast:15 row_mask:0xf bank_mask:0xf bound_ctrl:1
	v_sub_f32_e32 v94, v31, v87
	v_mul_f32_e32 v94, 0x3fb8aa3b, v94
	v_exp_f32_e32 v94, v94
	s_nop 0
	v_mul_f32_e32 v95, v94, v41
	v_mul_f32_e32 v94, v94, v49
	v_cvt_pk_bf16_f32 v95, v95, s0
	v_cvt_pk_bf16_f32 v94, v94, s0
	ds_write_b16 v109, v95 offset:5408
	ds_write_b16 v109, v94 offset:5416
	ds_write_b16 v108, v91 offset:10208
	s_and_saveexec_b64 s[58:59], s[40:41]
	s_cbranch_execz .LBB0_355
	v_mul_f32_e32 v87, 0xbfb8aa3b, v87
	v_exp_f32_e32 v87, v87
	v_lshl_add_u32 v91, v140, 2, v35
	ds_write_b32 v91, v87 offset:12844
.LBB0_355:
	s_or_b64 exec, exec, s[58:59]
	v_fmac_f32_e32 v188, v125, v68
	v_fmac_f32_e32 v188, v126, v72
	v_cvt_f32_f16_e32 v68, v32
	v_cvt_f32_f16_e32 v72, v38
	v_cvt_f32_f16_e32 v87, v42
	v_sub_f32_e32 v72, v72, v68
	v_fma_mix_f32 v94, v72, v76, v32 op_sel_hi:[0,0,1]
	v_cvt_f32_f16_e32 v72, v46
	v_sub_f32_e32 v68, v87, v68
	v_fmac_f32_e32 v94, v68, v80
	v_cvt_f32_f16_e32 v87, v50
	v_add_f32_dpp v68, v72, v72 row_shr:1 row_mask:0xf bank_mask:0xf bound_ctrl:1
	v_cvt_pk_bf16_f32 v94, v94, s0
	s_waitcnt vmcnt(0)
	v_mul_f32_e32 v76, v188, v250
	v_add_f32_dpp v68, v68, v68 row_shr:2 row_mask:0xf bank_mask:0xf bound_ctrl:1
	v_mul_f32_e32 v80, v118, v76
	v_mul_f32_e32 v76, v80, v87
	v_add_f32_dpp v68, v68, v68 row_shr:4 row_mask:0xf bank_mask:0xf bound_ctrl:1
	v_add_f32_e32 v87, -1.0, v87
	v_fma_f32 v87, v87, v174, 1.0
	v_add_f32_dpp v68, v68, v68 row_shr:8 row_mask:0xf bank_mask:0xf bound_ctrl:1
	v_mul_f32_e32 v87, v188, v87
	s_nop 0
	v_mov_b32_dpp v91, v68 row_newbcast:15 row_mask:0xf bank_mask:0xf bound_ctrl:1
	v_sub_f32_e32 v95, v68, v91
	v_mul_f32_e32 v95, 0x3fb8aa3b, v95
	v_exp_f32_e32 v95, v95
	s_nop 0
	v_mul_f32_e32 v97, v95, v76
	v_mul_f32_e32 v95, v95, v87
	v_cvt_pk_bf16_f32 v97, v97, s0
	v_cvt_pk_bf16_f32 v95, v95, s0
	ds_write_b16 v109, v97 offset:5488
	ds_write_b16 v109, v95 offset:5496
	ds_write_b16 v108, v94 offset:10256
	s_and_saveexec_b64 s[58:59], s[40:41]
	s_cbranch_execz .LBB0_357
	v_mul_f32_e32 v91, 0xbfb8aa3b, v91
	v_exp_f32_e32 v91, v91
	v_lshl_add_u32 v94, v140, 2, v35
	ds_write_b32 v94, v91 offset:12848
.LBB0_357:
	s_or_b64 exec, exec, s[58:59]
	v_fmac_f32_e32 v187, v123, v69
	v_cvt_f32_f16_sdwa v69, v32 dst_sel:DWORD dst_unused:UNUSED_PAD src0_sel:WORD_1
	v_cvt_f32_f16_sdwa v38, v38 dst_sel:DWORD dst_unused:UNUSED_PAD src0_sel:WORD_1
	v_cvt_f32_f16_sdwa v42, v42 dst_sel:DWORD dst_unused:UNUSED_PAD src0_sel:WORD_1
	v_fmac_f32_e32 v187, v124, v73
	v_cvt_f32_f16_sdwa v50, v50 dst_sel:DWORD dst_unused:UNUSED_PAD src0_sel:WORD_1
	v_sub_f32_e32 v38, v38, v69
	v_fma_mix_f32 v73, v38, v77, v32 op_sel:[0,0,1] op_sel_hi:[0,0,1]
	v_sub_f32_e32 v32, v42, v69
	v_cvt_f32_f16_sdwa v38, v46 dst_sel:DWORD dst_unused:UNUSED_PAD src0_sel:WORD_1
	v_fmac_f32_e32 v73, v32, v81
	v_cvt_pk_bf16_f32 v73, v73, s0
	v_add_f32_dpp v32, v38, v38 row_shr:1 row_mask:0xf bank_mask:0xf bound_ctrl:1
	s_waitcnt vmcnt(0)
	v_mul_f32_e32 v42, v187, v251
	v_add_f32_dpp v32, v32, v32 row_shr:2 row_mask:0xf bank_mask:0xf bound_ctrl:1
	v_mul_f32_e32 v46, v118, v42
	v_mul_f32_e32 v42, v46, v50
	v_add_f32_dpp v32, v32, v32 row_shr:4 row_mask:0xf bank_mask:0xf bound_ctrl:1
	v_add_f32_e32 v50, -1.0, v50
	s_waitcnt vmcnt(0)
	v_fma_f32 v50, v50, v175, 1.0
	v_add_f32_dpp v32, v32, v32 row_shr:8 row_mask:0xf bank_mask:0xf bound_ctrl:1
	v_mul_f32_e32 v50, v187, v50
	s_nop 0
	v_mov_b32_dpp v69, v32 row_newbcast:15 row_mask:0xf bank_mask:0xf bound_ctrl:1
	v_sub_f32_e32 v77, v32, v69
	v_mul_f32_e32 v77, 0x3fb8aa3b, v77
	v_exp_f32_e32 v77, v77
	s_nop 0
	v_mul_f32_e32 v81, v77, v42
	v_mul_f32_e32 v77, v77, v50
	v_cvt_pk_bf16_f32 v81, v81, s0
	v_cvt_pk_bf16_f32 v77, v77, s0
	ds_write_b16 v109, v81 offset:5568
	ds_write_b16 v109, v77 offset:5576
	ds_write_b16 v108, v73 offset:10304
	s_and_saveexec_b64 s[58:59], s[40:41]
	s_cbranch_execz .LBB0_359
	v_mul_f32_e32 v69, 0xbfb8aa3b, v69
	v_exp_f32_e32 v69, v69
	v_lshl_add_u32 v73, v140, 2, v35
	ds_write_b32 v73, v69 offset:12852
.LBB0_359:
	s_or_b64 exec, exec, s[58:59]
	v_fmac_f32_e32 v186, v121, v70
	v_cvt_f32_f16_e32 v69, v33
	v_cvt_f32_f16_e32 v70, v39
	v_cvt_f32_f16_e32 v73, v43
	v_cvt_f32_f16_e32 v77, v51
	v_fmac_f32_e32 v186, v122, v74
	v_sub_f32_e32 v70, v70, v69
	v_sub_f32_e32 v69, v73, v69
	v_fma_mix_f32 v81, v70, v78, v33 op_sel_hi:[0,0,1]
	v_fmac_f32_e32 v81, v69, v82
	v_cvt_f32_f16_e32 v70, v47
	v_cvt_pk_bf16_f32 v81, v81, s0
	s_waitcnt vmcnt(0)
	v_mul_f32_e32 v73, v186, v252
	v_add_f32_dpp v69, v70, v70 row_shr:1 row_mask:0xf bank_mask:0xf bound_ctrl:1
	v_mul_f32_e32 v74, v118, v73
	v_mul_f32_e32 v73, v74, v77
	v_add_f32_dpp v69, v69, v69 row_shr:2 row_mask:0xf bank_mask:0xf bound_ctrl:1
	v_add_f32_e32 v77, -1.0, v77
	s_waitcnt vmcnt(0)
	v_fma_f32 v77, v77, v176, 1.0
	v_add_f32_dpp v69, v69, v69 row_shr:4 row_mask:0xf bank_mask:0xf bound_ctrl:1
	v_mul_f32_e32 v77, v186, v77
	s_nop 0
	v_add_f32_dpp v69, v69, v69 row_shr:8 row_mask:0xf bank_mask:0xf bound_ctrl:1
	s_nop 1
	v_mov_b32_dpp v78, v69 row_newbcast:15 row_mask:0xf bank_mask:0xf bound_ctrl:1
	v_sub_f32_e32 v82, v69, v78
	v_mul_f32_e32 v82, 0x3fb8aa3b, v82
	v_exp_f32_e32 v82, v82
	s_nop 0
	v_mul_f32_e32 v91, v82, v73
	v_mul_f32_e32 v82, v82, v77
	v_cvt_pk_bf16_f32 v91, v91, s0
	v_cvt_pk_bf16_f32 v82, v82, s0
	ds_write_b16 v109, v91 offset:5648
	ds_write_b16 v109, v82 offset:5656
	ds_write_b16 v108, v81 offset:10352
	s_and_saveexec_b64 s[58:59], s[40:41]
	s_cbranch_execz .LBB0_361
	v_mul_f32_e32 v78, 0xbfb8aa3b, v78
	v_exp_f32_e32 v78, v78
	v_lshl_add_u32 v81, v140, 2, v35
	ds_write_b32 v81, v78 offset:12856
.LBB0_361:
	s_or_b64 exec, exec, s[58:59]
	v_fmac_f32_e32 v185, v119, v71
	v_cvt_f32_f16_sdwa v71, v33 dst_sel:DWORD dst_unused:UNUSED_PAD src0_sel:WORD_1
	v_cvt_f32_f16_sdwa v39, v39 dst_sel:DWORD dst_unused:UNUSED_PAD src0_sel:WORD_1
	v_fmac_f32_e32 v185, v120, v75
	v_cvt_f32_f16_sdwa v43, v43 dst_sel:DWORD dst_unused:UNUSED_PAD src0_sel:WORD_1
	v_sub_f32_e32 v39, v39, v71
	v_fma_mix_f32 v75, v39, v79, v33 op_sel:[0,0,1] op_sel_hi:[0,0,1]
	v_cvt_f32_f16_sdwa v39, v47 dst_sel:DWORD dst_unused:UNUSED_PAD src0_sel:WORD_1
	v_sub_f32_e32 v33, v43, v71
	v_fmac_f32_e32 v75, v33, v83
	v_cvt_f32_f16_sdwa v71, v51 dst_sel:DWORD dst_unused:UNUSED_PAD src0_sel:WORD_1
	v_add_f32_dpp v33, v39, v39 row_shr:1 row_mask:0xf bank_mask:0xf bound_ctrl:1
	v_cvt_pk_bf16_f32 v75, v75, s0
	s_waitcnt vmcnt(0)
	v_mul_f32_e32 v47, v185, v253
	v_add_f32_dpp v33, v33, v33 row_shr:2 row_mask:0xf bank_mask:0xf bound_ctrl:1
	v_mul_f32_e32 v51, v118, v47
	v_mul_f32_e32 v47, v51, v71
	v_add_f32_dpp v33, v33, v33 row_shr:4 row_mask:0xf bank_mask:0xf bound_ctrl:1
	v_add_f32_e32 v71, -1.0, v71
	v_fma_f32 v71, v71, v177, 1.0
	v_add_f32_dpp v33, v33, v33 row_shr:8 row_mask:0xf bank_mask:0xf bound_ctrl:1
	v_mul_f32_e32 v71, v185, v71
	s_nop 0
	v_mov_b32_dpp v43, v33 row_newbcast:15 row_mask:0xf bank_mask:0xf bound_ctrl:1
	v_sub_f32_e32 v78, v33, v43
	v_mul_f32_e32 v78, 0x3fb8aa3b, v78
	v_exp_f32_e32 v78, v78
	s_nop 0
	v_mul_f32_e32 v79, v78, v47
	v_mul_f32_e32 v78, v78, v71
	v_cvt_pk_bf16_f32 v79, v79, s0
	v_cvt_pk_bf16_f32 v78, v78, s0
	ds_write_b16 v109, v79 offset:5728
	ds_write_b16 v109, v78 offset:5736
	ds_write_b16 v108, v75 offset:10400
	s_and_saveexec_b64 s[58:59], s[40:41]
	s_cbranch_execz .LBB0_363
	v_mul_f32_e32 v43, 0xbfb8aa3b, v43
	v_exp_f32_e32 v43, v43
	v_lshl_add_u32 v75, v140, 2, v35
	ds_write_b32 v75, v43 offset:12860
.LBB0_363:
	s_or_b64 exec, exec, s[58:59]
	v_sub_f32_e32 v39, v39, v33
	v_mul_f32_e32 v39, 0x3fb8aa3b, v39
	v_exp_f32_e32 v39, v39
	v_cvt_f32_f16_sdwa v43, v21 dst_sel:DWORD dst_unused:UNUSED_PAD src0_sel:WORD_1
	v_cvt_f32_f16_sdwa v75, v25 dst_sel:DWORD dst_unused:UNUSED_PAD src0_sel:WORD_1
	v_cvt_f32_f16_e32 v25, v25
	v_mul_f32_e32 v39, v51, v39
	v_cvt_f32_f16_e32 v51, v21
	v_cvt_f32_f16_sdwa v78, v29 dst_sel:DWORD dst_unused:UNUSED_PAD src0_sel:WORD_1
	v_cvt_f32_f16_e32 v29, v29
	v_sub_f32_e32 v75, v75, v43
	v_sub_f32_e32 v25, v25, v51
	v_fma_mix_f32 v67, v75, v67, v21 op_sel:[0,0,1] op_sel_hi:[0,0,1]
	v_fma_mix_f32 v21, v25, v66, v21 op_sel_hi:[0,0,1]
	v_sub_f32_e32 v25, v29, v51
	v_mul_f32_e32 v29, 0xbfb8aa3b, v69
	v_exp_f32_e32 v29, v29
	v_fmac_f32_e32 v21, v25, v62
	v_cvt_f32_f16_sdwa v62, v24 dst_sel:DWORD dst_unused:UNUSED_PAD src0_sel:WORD_1
	v_cvt_f32_f16_sdwa v66, v28 dst_sel:DWORD dst_unused:UNUSED_PAD src0_sel:WORD_1
	v_mul_f32_e32 v29, v21, v29
	v_cvt_f32_f16_sdwa v21, v20 dst_sel:DWORD dst_unused:UNUSED_PAD src0_sel:WORD_1
	v_cvt_f32_f16_e32 v24, v24
	v_cvt_f32_f16_e32 v28, v28
	v_sub_f32_e32 v25, v70, v69
	v_sub_f32_e32 v62, v62, v21
	v_fma_mix_f32 v62, v62, v65, v20 op_sel:[0,0,1] op_sel_hi:[0,0,1]
	v_sub_f32_e32 v21, v66, v21
	v_fmac_f32_e32 v62, v21, v61
	v_sub_f32_e32 v21, v38, v32
	v_mul_f32_e32 v21, 0x3fb8aa3b, v21
	v_exp_f32_e32 v21, v21
	v_mul_f32_e32 v38, 0xbfb8aa3b, v32
	v_mul_f32_e32 v32, 0x3fb8aa3b, v32
	v_exp_f32_e32 v32, v32
	v_mul_f32_e32 v21, v46, v21
	v_cvt_f32_f16_e32 v46, v20
	v_cvt_f32_f16_sdwa v61, v27 dst_sel:DWORD dst_unused:UNUSED_PAD src0_sel:WORD_1
	v_mul_f32_e32 v42, v32, v42
	v_mul_f32_e32 v32, v32, v50
	v_sub_f32_e32 v24, v24, v46
	v_fma_mix_f32 v20, v24, v64, v20 op_sel_hi:[0,0,1]
	v_sub_f32_e32 v24, v28, v46
	v_mul_f32_e32 v28, 0xbfb8aa3b, v68
	v_exp_f32_e32 v28, v28
	v_fmac_f32_e32 v20, v24, v60
	v_cvt_f32_f16_sdwa v50, v23 dst_sel:DWORD dst_unused:UNUSED_PAD src0_sel:WORD_1
	v_cvt_f32_f16_e32 v23, v23
	v_mul_f32_e32 v28, v20, v28
	v_cvt_f32_f16_sdwa v20, v19 dst_sel:DWORD dst_unused:UNUSED_PAD src0_sel:WORD_1
	v_cvt_f32_f16_e32 v27, v27
	v_sub_f32_e32 v24, v72, v68
	v_sub_f32_e32 v43, v78, v43
	v_sub_f32_e32 v50, v50, v20
	v_fma_mix_f32 v50, v50, v59, v19 op_sel:[0,0,1] op_sel_hi:[0,0,1]
	v_sub_f32_e32 v20, v61, v20
	v_fmac_f32_e32 v50, v20, v55
	v_sub_f32_e32 v20, v37, v31
	v_mul_f32_e32 v20, 0x3fb8aa3b, v20
	v_exp_f32_e32 v20, v20
	v_mul_f32_e32 v37, 0xbfb8aa3b, v31
	v_mul_f32_e32 v31, 0x3fb8aa3b, v31
	v_exp_f32_e32 v31, v31
	v_mul_f32_e32 v20, v45, v20
	v_cvt_f32_f16_e32 v45, v19
	v_mul_f32_e32 v25, 0x3fb8aa3b, v25
	v_mul_f32_e32 v41, v31, v41
	v_mul_f32_e32 v31, v31, v49
	v_sub_f32_e32 v23, v23, v45
	v_fma_mix_f32 v19, v23, v58, v19 op_sel_hi:[0,0,1]
	v_sub_f32_e32 v23, v27, v45
	v_mul_f32_e32 v27, 0xbfb8aa3b, v85
	v_exp_f32_e32 v27, v27
	v_fmac_f32_e32 v19, v23, v54
	v_cvt_f32_f16_sdwa v49, v22 dst_sel:DWORD dst_unused:UNUSED_PAD src0_sel:WORD_1
	v_cvt_f32_f16_sdwa v54, v26 dst_sel:DWORD dst_unused:UNUSED_PAD src0_sel:WORD_1
	v_mul_f32_e32 v27, v19, v27
	v_cvt_f32_f16_sdwa v19, v18 dst_sel:DWORD dst_unused:UNUSED_PAD src0_sel:WORD_1
	v_cvt_f32_f16_e32 v22, v22
	v_cvt_f32_f16_e32 v26, v26
	v_sub_f32_e32 v23, v86, v85
	v_sub_f32_e32 v49, v49, v19
	v_fma_mix_f32 v49, v49, v57, v18 op_sel:[0,0,1] op_sel_hi:[0,0,1]
	v_sub_f32_e32 v19, v54, v19
	v_fmac_f32_e32 v49, v19, v53
	v_sub_f32_e32 v19, v36, v30
	v_mul_f32_e32 v19, 0x3fb8aa3b, v19
	v_exp_f32_e32 v19, v19
	v_mul_f32_e32 v36, 0xbfb8aa3b, v30
	v_mul_f32_e32 v30, 0x3fb8aa3b, v30
	v_exp_f32_e32 v30, v30
	v_mul_f32_e32 v19, v44, v19
	v_cvt_f32_f16_e32 v44, v18
	v_mul_f32_e32 v24, 0x3fb8aa3b, v24
	v_mul_f32_e32 v23, 0x3fb8aa3b, v23
	v_fmac_f32_e32 v67, v43, v63
	v_sub_f32_e32 v22, v22, v44
	v_fma_mix_f32 v18, v22, v56, v18 op_sel_hi:[0,0,1]
	v_sub_f32_e32 v22, v26, v44
	v_sub_f32_e32 v44, v88, v92
	v_mul_f32_e32 v44, 0x3fb8aa3b, v44
	v_mul_f32_e32 v43, 0xbfb8aa3b, v33
	v_exp_f32_e32 v25, v25
	v_exp_f32_e32 v24, v24
	v_exp_f32_e32 v23, v23
	v_mul_f32_e32 v40, v30, v40
	v_mul_f32_e32 v30, v30, v48
	v_exp_f32_e32 v44, v44
	v_mul_f32_e32 v48, 0xbfb8aa3b, v92
	v_exp_f32_e32 v43, v43
	v_mul_f32_e32 v33, 0x3fb8aa3b, v33
	v_mul_f32_e32 v51, 0x3fb8aa3b, v69
	v_exp_f32_e32 v38, v38
	v_mul_f32_e32 v46, 0x3fb8aa3b, v68
	v_exp_f32_e32 v37, v37
	v_mul_f32_e32 v45, 0x3fb8aa3b, v85
	v_exp_f32_e32 v36, v36
	v_mul_f32_e32 v26, 0x3fb8aa3b, v92
	v_exp_f32_e32 v48, v48
	v_exp_f32_e32 v33, v33
	v_exp_f32_e32 v51, v51
	v_exp_f32_e32 v46, v46
	v_exp_f32_e32 v45, v45
	v_exp_f32_e32 v26, v26
	v_mul_f32_e32 v25, v74, v25
	v_mul_f32_e32 v24, v80, v24
	v_mul_f32_e32 v23, v90, v23
	v_fmac_f32_e32 v18, v22, v52
	v_mul_f32_e32 v22, v96, v44
	v_mul_f32_e32 v43, v67, v43
	v_mul_f32_e32 v38, v62, v38
	v_mul_f32_e32 v37, v50, v37
	v_mul_f32_e32 v36, v49, v36
	v_mul_f32_e32 v44, v18, v48
	v_cvt_pk_bf16_f32 v18, v22, v19
	v_cvt_pk_bf16_f32 v19, v23, v20
	v_cvt_pk_bf16_f32 v20, v24, v21
	v_cvt_pk_bf16_f32 v21, v25, v39
	v_mul_f32_e32 v47, v33, v47
	v_mul_f32_e32 v63, v51, v73
	v_mul_f32_e32 v60, v46, v76
	v_mul_f32_e32 v50, v45, v89
	v_mul_f32_e32 v48, v26, v84
	ds_write_b128 v102, v[18:21] offset:16
	v_cvt_pk_bf16_f32 v18, v44, v36
	v_cvt_pk_bf16_f32 v19, v27, v37
	v_cvt_pk_bf16_f32 v20, v28, v38
	v_cvt_pk_bf16_f32 v21, v29, v43
	v_mul_f32_e32 v33, v33, v71
	v_mul_f32_e32 v51, v51, v77
	v_mul_f32_e32 v46, v46, v87
	v_mul_f32_e32 v45, v45, v93
	v_mul_f32_e32 v26, v26, v103
	ds_write_b128 v102, v[18:21] offset:2320
	v_cvt_pk_bf16_f32 v18, v48, v40
	v_cvt_pk_bf16_f32 v19, v50, v41
	v_cvt_pk_bf16_f32 v20, v60, v42
	v_cvt_pk_bf16_f32 v21, v63, v47
	ds_write_b128 v162, v[18:21] offset:16
	v_cvt_pk_bf16_f32 v18, v26, v30
	v_cvt_pk_bf16_f32 v19, v45, v31
	v_cvt_pk_bf16_f32 v20, v46, v32
	v_cvt_pk_bf16_f32 v21, v51, v33
	ds_write_b128 v162, v[18:21] offset:2320
	s_add_i32 s98, s97, 1
	s_cmp_ge_i32 s98, s96
	s_cbranch_scc1 .Lspf_skip1
	v_lshl_add_u32 v22, s98, 6, v151
	v_sub_u32_e32 v23, 0x7ff, v22
	v_cndmask_b32_e64 v24, v23, v22, s[56:57]
	v_ashrrev_i32_e32 v25, 31, v24
	v_lshl_add_u64 v[22:23], s[22:23], 0, v[24:25]
	v_mov_b64_e32 v[26:27], s[30:31]
	v_mad_u64_u32 v[28:29], s[100:101], v22, s89, v[26:27]
	v_mad_i32_i24 v29, v23, s89, v29
	v_lshlrev_b32_e32 v30, 1, v148
	v_mov_b32_e32 v31, v34
	v_lshl_add_u64 v[28:29], v[28:29], 0, v[30:31]
	s_mov_b64 s[100:101], 0x1000
	v_lshl_add_u64 v[30:31], v[28:29], 0, s[100:101]
	s_mov_b64 s[100:101], 0x3000
	v_lshl_add_u64 v[32:33], v[28:29], 0, s[100:101]
	v_lshl_add_u64 v[22:23], v[22:23], 0, s[24:25]
	v_lshlrev_b64 v[22:23], 10, v[22:23]
	v_lshl_add_u64 v[26:27], v[154:155], 0, v[22:23]
	v_lshl_add_u64 v[22:23], v[156:157], 0, v[22:23]
	v_mov_b32_e32 v56, 0
	v_mov_b32_e32 v57, 0
	v_mov_b32_e32 v58, 0
	v_mov_b32_e32 v59, 0
	v_mov_b32_e32 v60, 0
	v_mov_b32_e32 v61, 0
	v_mov_b32_e32 v62, 0
	v_mov_b32_e32 v63, 0
	v_mov_b32_e32 v68, 0
	v_mov_b32_e32 v69, 0
	v_mov_b32_e32 v70, 0
	v_mov_b32_e32 v71, 0
	v_mov_b32_e32 v72, 0
	v_mov_b32_e32 v73, 0
	v_mov_b32_e32 v74, 0
	v_mov_b32_e32 v75, 0
	v_mov_b32_e32 v92, 0
	v_mov_b32_e32 v93, 0
	v_mov_b32_e32 v94, 0
	v_mov_b32_e32 v95, 0
	v_mov_b32_e32 v96, 0
	v_mov_b32_e32 v97, 0
	v_mov_b32_e32 v98, 0
	v_mov_b32_e32 v99, 0
	v_mov_b32_e32 v100, 0
	v_mov_b32_e32 v101, 0
	v_mov_b32_e32 v102, 0
	v_mov_b32_e32 v103, 0
	v_mov_b32_e32 v104, 0
	v_mov_b32_e32 v105, 0
	v_mov_b32_e32 v106, 0
	v_mov_b32_e32 v107, 0
	global_load_dwordx4 v[84:87], v[30:31], off offset:1024
	global_load_dwordx4 v[88:91], v[30:31], off offset:1040
	global_load_dwordx4 v[52:55], v[30:31], off
	global_load_dwordx4 v[64:67], v[30:31], off offset:2048
	global_load_dwordx4 v[76:79], v[26:27], off
	global_load_dwordx4 v[80:83], v[22:23], off
	v_cmp_lt_i32_e32 vcc, 0, v24
	s_and_saveexec_b64 s[100:101], vcc
	global_load_dwordx4 v[96:99], v[28:29], off offset:-2816
	global_load_dwordx4 v[104:107], v[28:29], off offset:-2800
	global_load_dwordx4 v[56:59], v[28:29], off offset:-3840
	global_load_dwordx4 v[68:71], v[28:29], off offset:-1792
	s_mov_b64 exec, s[100:101]
	v_cmp_gt_i32_e32 vcc, 0x7ff, v24
	s_and_saveexec_b64 s[100:101], vcc
	global_load_dwordx4 v[92:95], v[32:33], off offset:768
	global_load_dwordx4 v[100:103], v[32:33], off offset:784
	global_load_dwordx4 v[60:63], v[32:33], off offset:-256
	global_load_dwordx4 v[72:75], v[32:33], off offset:1792
	s_mov_b64 exec, s[100:101]
